# waitcnt placement on the first-unit path: the compiler's vmcnt waits in the accumulator-zeroing blocks removed (all GEMM phases), with the barrier-first unit boundary and no setprio
# baseline (speedup 1.0000x reference)
.LBB0_142:
	s_lshl_b32 s86, s85, 20
	s_and_b64 s[0:1], s[40:41], exec
	s_cselect_b32 s0, s86, s4
	s_lshl_b32 s87, s84, 20
	s_and_b64 s[6:7], s[40:41], exec
	s_cselect_b32 s1, s87, s5
	s_add_i32 s4, s4, 0x84000
	s_add_i32 s5, s5, 0x8000
	s_mov_b32 s6, -2
	s_cmp_eq_u32 s82, 1
	s_cbranch_scc0 .Lpeel_p1
	v_mov_b32_e32 v0, 0
	v_mov_b32_e32 v1, v0
	v_mov_b32_e32 v2, v0
	v_mov_b32_e32 v3, v0
	v_mov_b32_e32 v8, v0
	v_mov_b32_e32 v9, v0
	v_mov_b32_e32 v10, v0
	v_mov_b32_e32 v11, v0
	v_mov_b32_e32 v32, v0
	v_mov_b32_e32 v33, v0
	v_mov_b32_e32 v34, v0
	v_mov_b32_e32 v35, v0
	v_mov_b32_e32 v40, v0
	v_mov_b32_e32 v41, v0
	v_mov_b32_e32 v42, v0
	v_mov_b32_e32 v43, v0
	v_mov_b32_e32 v48, v0
	v_mov_b32_e32 v49, v0
	v_mov_b32_e32 v50, v0
	v_mov_b32_e32 v51, v0
	v_mov_b32_e32 v56, v0
	v_mov_b32_e32 v57, v0
	v_mov_b32_e32 v58, v0
	v_mov_b32_e32 v59, v0
	v_mov_b32_e32 v64, v0
	v_mov_b32_e32 v65, v0
	v_mov_b32_e32 v66, v0
	v_mov_b32_e32 v67, v0
	v_mov_b32_e32 v72, v0
	v_mov_b32_e32 v73, v0
	v_mov_b32_e32 v74, v0
	v_mov_b32_e32 v75, v0
	v_mov_b32_e32 v4, v0
	v_mov_b32_e32 v5, v0
	v_mov_b32_e32 v6, v0
	v_mov_b32_e32 v7, v0
	v_mov_b32_e32 v12, v0
	v_mov_b32_e32 v13, v0
	v_mov_b32_e32 v14, v0
	v_mov_b32_e32 v15, v0
	v_mov_b32_e32 v36, v0
	v_mov_b32_e32 v37, v0
	v_mov_b32_e32 v38, v0
	v_mov_b32_e32 v39, v0
	v_mov_b32_e32 v44, v0
	v_mov_b32_e32 v45, v0
	v_mov_b32_e32 v46, v0
	v_mov_b32_e32 v47, v0
	v_mov_b32_e32 v52, v0
	v_mov_b32_e32 v53, v0
	v_mov_b32_e32 v54, v0
	v_mov_b32_e32 v55, v0
	v_mov_b32_e32 v60, v0
	v_mov_b32_e32 v61, v0
	v_mov_b32_e32 v62, v0
	v_mov_b32_e32 v63, v0
	v_mov_b32_e32 v68, v0
	v_mov_b32_e32 v69, v0
	v_mov_b32_e32 v70, v0
	v_mov_b32_e32 v71, v0
	v_mov_b32_e32 v76, v0
	v_mov_b32_e32 v77, v0
	v_mov_b32_e32 v78, v0
	v_mov_b32_e32 v79, v0
	v_mov_b32_e32 v104, v0
	v_mov_b32_e32 v105, v0
	v_mov_b32_e32 v106, v0
	v_mov_b32_e32 v107, v0
	v_mov_b32_e32 v112, v0
	v_mov_b32_e32 v113, v0
	v_mov_b32_e32 v114, v0
	v_mov_b32_e32 v115, v0
	v_mov_b32_e32 v120, v0
	v_mov_b32_e32 v121, v0
	v_mov_b32_e32 v122, v0
	v_mov_b32_e32 v123, v0
	v_mov_b32_e32 v128, v0
	v_mov_b32_e32 v129, v0
	v_mov_b32_e32 v130, v0
	v_mov_b32_e32 v131, v0
	v_mov_b32_e32 v136, v0
	v_mov_b32_e32 v137, v0
	v_mov_b32_e32 v138, v0
	v_mov_b32_e32 v139, v0
	v_mov_b32_e32 v144, v0
	v_mov_b32_e32 v145, v0
	v_mov_b32_e32 v146, v0
	v_mov_b32_e32 v147, v0
	v_mov_b32_e32 v156, v0
	v_mov_b32_e32 v157, v0
	v_mov_b32_e32 v158, v0
	v_mov_b32_e32 v159, v0
	v_mov_b32_e32 v172, v0
	v_mov_b32_e32 v173, v0
	v_mov_b32_e32 v174, v0
	v_mov_b32_e32 v175, v0
	v_mov_b32_e32 v108, v0
	v_mov_b32_e32 v109, v0
	v_mov_b32_e32 v110, v0
	v_mov_b32_e32 v111, v0
	v_mov_b32_e32 v116, v0
	v_mov_b32_e32 v117, v0
	v_mov_b32_e32 v118, v0
	v_mov_b32_e32 v119, v0
	v_mov_b32_e32 v124, v0
	v_mov_b32_e32 v125, v0
	v_mov_b32_e32 v126, v0
	v_mov_b32_e32 v127, v0
	v_mov_b32_e32 v132, v0
	v_mov_b32_e32 v133, v0
	v_mov_b32_e32 v134, v0
	v_mov_b32_e32 v135, v0
	v_mov_b32_e32 v140, v0
	v_mov_b32_e32 v141, v0
	v_mov_b32_e32 v142, v0
	v_mov_b32_e32 v143, v0
	v_mov_b32_e32 v148, v0
	v_mov_b32_e32 v149, v0
	v_mov_b32_e32 v150, v0
	v_mov_b32_e32 v151, v0
	v_mov_b32_e32 v164, v0
	v_mov_b32_e32 v165, v0
	v_mov_b32_e32 v166, v0
	v_mov_b32_e32 v167, v0
	v_mov_b32_e32 v180, v0
	v_mov_b32_e32 v181, v0
	v_mov_b32_e32 v182, v0
	v_mov_b32_e32 v183, v0
	s_branch .LBB0_143

.LBB0_593:
	v_writelane_b32 v254, s3, 27
	s_lshl_b32 s1, s3, 20
	v_writelane_b32 v254, s1, 29
	s_and_b64 s[2:3], s[10:11], exec
	v_writelane_b32 v254, s6, 25
	s_cselect_b32 vcc_lo, s1, s96
	s_lshl_b32 s1, s6, 20
	v_writelane_b32 v254, s10, 23
	s_and_b64 s[2:3], s[10:11], exec
	s_cselect_b32 vcc_hi, s1, s38
	v_writelane_b32 v254, s11, 24
	v_writelane_b32 v254, s1, 31
	s_lshl_b32 s1, s0, 20
	s_lshl_b32 s0, s92, 17
	s_add_i32 s91, s1, s0
	v_writelane_b32 v254, s1, 33
	s_or_b32 s90, s91, 0x10000
	s_or_b32 s88, s91, 0x2000
	s_or_b32 s81, s91, 0x12000
	s_or_b32 s80, s91, 0x4000
	s_or_b32 s89, s91, 0x14000
	s_or_b32 s33, s91, 0x6000
	s_or_b32 s3, s91, 0x16000
	s_or_b32 s2, s91, 0x8000
	s_or_b32 s1, s91, 0x18000
	s_or_b32 s0, s91, 0xa000
	s_or_b32 s37, s91, 0x1a000
	s_or_b32 s52, s91, 0xc000
	s_or_b32 s56, s91, 0x1c000
	s_or_b32 s39, s91, 0xe000
	s_or_b32 s36, s91, 0x1e000
	v_readlane_b32 s70, v251, 1
	v_readlane_b32 s71, v251, 2
	s_add_u32 s4, s70, s91
	s_addc_u32 s5, s71, 0
	s_add_u32 s6, s70, s90
	s_addc_u32 s7, s71, 0
	s_add_u32 s8, s70, s88
	s_addc_u32 s9, s71, 0
	s_add_u32 s10, s70, s81
	s_addc_u32 s11, s71, 0
	s_add_u32 s12, s70, s80
	s_addc_u32 s13, s71, 0
	s_add_u32 s14, s70, s89
	s_addc_u32 s15, s71, 0
	s_add_u32 s16, s70, s33
	s_addc_u32 s17, s71, 0
	s_add_u32 s18, s70, s3
	s_addc_u32 s19, s71, 0
	s_add_u32 s28, s70, s2
	s_addc_u32 s29, s71, 0
	s_add_u32 s40, s70, s1
	s_addc_u32 s41, s71, 0
	s_add_u32 s42, s70, s0
	s_addc_u32 s43, s71, 0
	s_add_u32 s44, s70, s37
	s_addc_u32 s45, s71, 0
	v_writelane_b32 v254, s52, 41
	s_add_u32 s52, s70, s52
	s_addc_u32 s53, s71, 0
	v_writelane_b32 v254, s56, 39
	s_add_u32 s56, s70, s56
	s_addc_u32 s57, s71, 0
	s_add_u32 s68, s70, s39
	s_addc_u32 s69, s71, 0
	v_mov_b32_e32 v80, v81
	v_mov_b32_e32 v82, v81
	v_mov_b32_e32 v83, v81
	v_writelane_b32 v254, s39, 37
	s_add_u32 s70, s70, s36
	v_mov_b64_e32 v[0:1], v[80:81]
	v_mov_b64_e32 v[4:5], v[80:81]
	v_mov_b64_e32 v[16:17], v[80:81]
	v_mov_b64_e32 v[20:21], v[80:81]
	v_mov_b64_e32 v[32:33], v[80:81]
	v_mov_b64_e32 v[36:37], v[80:81]
	v_mov_b64_e32 v[48:49], v[80:81]
	v_mov_b64_e32 v[52:53], v[80:81]
	v_mov_b64_e32 v[8:9], v[80:81]
	v_mov_b64_e32 v[12:13], v[80:81]
	v_mov_b64_e32 v[24:25], v[80:81]
	v_mov_b64_e32 v[28:29], v[80:81]
	v_mov_b64_e32 v[40:41], v[80:81]
	v_mov_b64_e32 v[44:45], v[80:81]
	v_mov_b64_e32 v[56:57], v[80:81]
	v_mov_b64_e32 v[60:61], v[80:81]
	v_mov_b64_e32 v[64:65], v[80:81]
	v_mov_b64_e32 v[68:69], v[80:81]
	v_mov_b64_e32 v[106:107], v[82:83]
	v_mov_b64_e32 v[110:111], v[82:83]
	v_mov_b64_e32 v[122:123], v[82:83]
	v_mov_b64_e32 v[126:127], v[82:83]
	v_mov_b64_e32 v[138:139], v[82:83]
	v_mov_b64_e32 v[142:143], v[82:83]
	v_mov_b64_e32 v[72:73], v[80:81]
	v_mov_b64_e32 v[76:77], v[80:81]
	v_mov_b64_e32 v[114:115], v[82:83]
	v_mov_b64_e32 v[118:119], v[82:83]
	v_mov_b64_e32 v[130:131], v[82:83]
	v_mov_b64_e32 v[134:135], v[82:83]
	v_mov_b64_e32 v[146:147], v[82:83]
	v_mov_b64_e32 v[150:151], v[82:83]
	v_writelane_b32 v254, s36, 35
	s_addc_u32 s71, s71, 0
	s_add_i32 s93, s38, 0x8000
	s_mov_b32 s38, -2
	s_mov_b32 s39, 0
	v_mov_b64_e32 v[2:3], v[82:83]
	v_mov_b64_e32 v[6:7], v[82:83]
	v_mov_b64_e32 v[18:19], v[82:83]
	v_mov_b64_e32 v[22:23], v[82:83]
	v_mov_b64_e32 v[34:35], v[82:83]
	v_mov_b64_e32 v[38:39], v[82:83]
	v_mov_b64_e32 v[50:51], v[82:83]
	v_mov_b64_e32 v[54:55], v[82:83]
	v_mov_b64_e32 v[10:11], v[82:83]
	v_mov_b64_e32 v[14:15], v[82:83]
	v_mov_b64_e32 v[26:27], v[82:83]
	v_mov_b64_e32 v[30:31], v[82:83]
	v_mov_b64_e32 v[42:43], v[82:83]
	v_mov_b64_e32 v[46:47], v[82:83]
	v_mov_b64_e32 v[58:59], v[82:83]
	v_mov_b64_e32 v[62:63], v[82:83]
	v_mov_b64_e32 v[66:67], v[82:83]
	v_mov_b64_e32 v[70:71], v[82:83]
	v_mov_b64_e32 v[104:105], v[80:81]
	v_mov_b64_e32 v[108:109], v[80:81]
	v_mov_b64_e32 v[120:121], v[80:81]
	v_mov_b64_e32 v[124:125], v[80:81]
	v_mov_b64_e32 v[136:137], v[80:81]
	v_mov_b64_e32 v[140:141], v[80:81]
	v_mov_b64_e32 v[74:75], v[82:83]
	v_mov_b64_e32 v[78:79], v[82:83]
	v_mov_b64_e32 v[112:113], v[80:81]
	v_mov_b64_e32 v[116:117], v[80:81]
	v_mov_b64_e32 v[128:129], v[80:81]
	v_mov_b64_e32 v[132:133], v[80:81]
	v_mov_b64_e32 v[144:145], v[80:81]
	v_mov_b64_e32 v[148:149], v[80:81]
	s_branch .LBB0_595

.LBB0_690:
	s_lshl_b32 s94, s92, 20
	s_and_b64 s[6:7], s[40:41], exec
	s_cselect_b32 s6, s94, s8
	s_lshl_b32 s95, s93, 20
	s_and_b64 s[10:11], s[40:41], exec
	s_cselect_b32 s7, s95, s9
	s_add_i32 s8, s8, 0x84000
	s_add_i32 s9, s9, 0x8000
	s_mov_b32 s10, -2
	s_cmp_eq_u32 s90, 1
	s_cbranch_scc0 .Lpeel_p4
	v_mov_b32_e32 v0, 0
	v_mov_b32_e32 v1, v0
	v_mov_b32_e32 v2, v0
	v_mov_b32_e32 v3, v0
	v_mov_b32_e32 v4, v0
	v_mov_b32_e32 v5, v0
	v_mov_b32_e32 v6, v0
	v_mov_b32_e32 v7, v0
	v_mov_b32_e32 v16, v0
	v_mov_b32_e32 v17, v0
	v_mov_b32_e32 v18, v0
	v_mov_b32_e32 v19, v0
	v_mov_b32_e32 v20, v0
	v_mov_b32_e32 v21, v0
	v_mov_b32_e32 v22, v0
	v_mov_b32_e32 v23, v0
	v_mov_b32_e32 v32, v0
	v_mov_b32_e32 v33, v0
	v_mov_b32_e32 v34, v0
	v_mov_b32_e32 v35, v0
	v_mov_b32_e32 v36, v0
	v_mov_b32_e32 v37, v0
	v_mov_b32_e32 v38, v0
	v_mov_b32_e32 v39, v0
	v_mov_b32_e32 v48, v0
	v_mov_b32_e32 v49, v0
	v_mov_b32_e32 v50, v0
	v_mov_b32_e32 v51, v0
	v_mov_b32_e32 v52, v0
	v_mov_b32_e32 v53, v0
	v_mov_b32_e32 v54, v0
	v_mov_b32_e32 v55, v0
	v_mov_b32_e32 v8, v0
	v_mov_b32_e32 v9, v0
	v_mov_b32_e32 v10, v0
	v_mov_b32_e32 v11, v0
	v_mov_b32_e32 v12, v0
	v_mov_b32_e32 v13, v0
	v_mov_b32_e32 v14, v0
	v_mov_b32_e32 v15, v0
	v_mov_b32_e32 v24, v0
	v_mov_b32_e32 v25, v0
	v_mov_b32_e32 v26, v0
	v_mov_b32_e32 v27, v0
	v_mov_b32_e32 v28, v0
	v_mov_b32_e32 v29, v0
	v_mov_b32_e32 v30, v0
	v_mov_b32_e32 v31, v0
	v_mov_b32_e32 v40, v0
	v_mov_b32_e32 v41, v0
	v_mov_b32_e32 v42, v0
	v_mov_b32_e32 v43, v0
	v_mov_b32_e32 v44, v0
	v_mov_b32_e32 v45, v0
	v_mov_b32_e32 v46, v0
	v_mov_b32_e32 v47, v0
	v_mov_b32_e32 v56, v0
	v_mov_b32_e32 v57, v0
	v_mov_b32_e32 v58, v0
	v_mov_b32_e32 v59, v0
	v_mov_b32_e32 v60, v0
	v_mov_b32_e32 v61, v0
	v_mov_b32_e32 v62, v0
	v_mov_b32_e32 v63, v0
	v_mov_b32_e32 v64, v0
	v_mov_b32_e32 v65, v0
	v_mov_b32_e32 v66, v0
	v_mov_b32_e32 v67, v0
	v_mov_b32_e32 v68, v0
	v_mov_b32_e32 v69, v0
	v_mov_b32_e32 v70, v0
	v_mov_b32_e32 v71, v0
	v_mov_b32_e32 v104, v0
	v_mov_b32_e32 v105, v0
	v_mov_b32_e32 v106, v0
	v_mov_b32_e32 v107, v0
	v_mov_b32_e32 v108, v0
	v_mov_b32_e32 v109, v0
	v_mov_b32_e32 v110, v0
	v_mov_b32_e32 v111, v0
	v_mov_b32_e32 v120, v0
	v_mov_b32_e32 v121, v0
	v_mov_b32_e32 v122, v0
	v_mov_b32_e32 v123, v0
	v_mov_b32_e32 v124, v0
	v_mov_b32_e32 v125, v0
	v_mov_b32_e32 v126, v0
	v_mov_b32_e32 v127, v0
	v_mov_b32_e32 v144, v0
	v_mov_b32_e32 v145, v0
	v_mov_b32_e32 v146, v0
	v_mov_b32_e32 v147, v0
	v_mov_b32_e32 v148, v0
	v_mov_b32_e32 v149, v0
	v_mov_b32_e32 v150, v0
	v_mov_b32_e32 v151, v0
	v_mov_b32_e32 v72, v0
	v_mov_b32_e32 v73, v0
	v_mov_b32_e32 v74, v0
	v_mov_b32_e32 v75, v0
	v_mov_b32_e32 v76, v0
	v_mov_b32_e32 v77, v0
	v_mov_b32_e32 v78, v0
	v_mov_b32_e32 v79, v0
	v_mov_b32_e32 v112, v0
	v_mov_b32_e32 v113, v0
	v_mov_b32_e32 v114, v0
	v_mov_b32_e32 v115, v0
	v_mov_b32_e32 v116, v0
	v_mov_b32_e32 v117, v0
	v_mov_b32_e32 v118, v0
	v_mov_b32_e32 v119, v0
	v_mov_b32_e32 v132, v0
	v_mov_b32_e32 v133, v0
	v_mov_b32_e32 v134, v0
	v_mov_b32_e32 v135, v0
	v_mov_b32_e32 v136, v0
	v_mov_b32_e32 v137, v0
	v_mov_b32_e32 v138, v0
	v_mov_b32_e32 v139, v0
	v_mov_b32_e32 v160, v0
	v_mov_b32_e32 v161, v0
	v_mov_b32_e32 v162, v0
	v_mov_b32_e32 v163, v0
	v_mov_b32_e32 v164, v0
	v_mov_b32_e32 v165, v0
	v_mov_b32_e32 v166, v0
	v_mov_b32_e32 v167, v0
	s_branch .LBB0_691

.LBB0_794:
	s_lshl_b32 s48, s45, 20
	s_and_b64 s[4:5], s[38:39], exec
	s_cselect_b32 s4, s48, s37
	s_lshl_b32 s49, s44, 20
	s_and_b64 s[52:53], s[38:39], exec
	s_cselect_b32 s5, s49, s51
	s_add_i32 s37, s37, 0x84000
	s_add_i32 s51, s51, 0x8000
	s_mov_b32 s52, -2
	s_cmp_eq_u32 s43, 1
	s_cbranch_scc0 .Lpeel_p5
	v_mov_b32_e32 v0, 0
	v_mov_b32_e32 v1, v0
	v_mov_b32_e32 v2, v0
	v_mov_b32_e32 v3, v0
	v_mov_b32_e32 v8, v0
	v_mov_b32_e32 v9, v0
	v_mov_b32_e32 v10, v0
	v_mov_b32_e32 v11, v0
	v_mov_b32_e32 v16, v0
	v_mov_b32_e32 v17, v0
	v_mov_b32_e32 v18, v0
	v_mov_b32_e32 v19, v0
	v_mov_b32_e32 v24, v0
	v_mov_b32_e32 v25, v0
	v_mov_b32_e32 v26, v0
	v_mov_b32_e32 v27, v0
	v_mov_b32_e32 v32, v0
	v_mov_b32_e32 v33, v0
	v_mov_b32_e32 v34, v0
	v_mov_b32_e32 v35, v0
	v_mov_b32_e32 v40, v0
	v_mov_b32_e32 v41, v0
	v_mov_b32_e32 v42, v0
	v_mov_b32_e32 v43, v0
	v_mov_b32_e32 v48, v0
	v_mov_b32_e32 v49, v0
	v_mov_b32_e32 v50, v0
	v_mov_b32_e32 v51, v0
	v_mov_b32_e32 v56, v0
	v_mov_b32_e32 v57, v0
	v_mov_b32_e32 v58, v0
	v_mov_b32_e32 v59, v0
	v_mov_b32_e32 v4, v0
	v_mov_b32_e32 v5, v0
	v_mov_b32_e32 v6, v0
	v_mov_b32_e32 v7, v0
	v_mov_b32_e32 v12, v0
	v_mov_b32_e32 v13, v0
	v_mov_b32_e32 v14, v0
	v_mov_b32_e32 v15, v0
	v_mov_b32_e32 v20, v0
	v_mov_b32_e32 v21, v0
	v_mov_b32_e32 v22, v0
	v_mov_b32_e32 v23, v0
	v_mov_b32_e32 v28, v0
	v_mov_b32_e32 v29, v0
	v_mov_b32_e32 v30, v0
	v_mov_b32_e32 v31, v0
	v_mov_b32_e32 v36, v0
	v_mov_b32_e32 v37, v0
	v_mov_b32_e32 v38, v0
	v_mov_b32_e32 v39, v0
	v_mov_b32_e32 v44, v0
	v_mov_b32_e32 v45, v0
	v_mov_b32_e32 v46, v0
	v_mov_b32_e32 v47, v0
	v_mov_b32_e32 v52, v0
	v_mov_b32_e32 v53, v0
	v_mov_b32_e32 v54, v0
	v_mov_b32_e32 v55, v0
	v_mov_b32_e32 v60, v0
	v_mov_b32_e32 v61, v0
	v_mov_b32_e32 v62, v0
	v_mov_b32_e32 v63, v0
	v_mov_b32_e32 v64, v0
	v_mov_b32_e32 v65, v0
	v_mov_b32_e32 v66, v0
	v_mov_b32_e32 v67, v0
	v_mov_b32_e32 v72, v0
	v_mov_b32_e32 v73, v0
	v_mov_b32_e32 v74, v0
	v_mov_b32_e32 v75, v0
	v_mov_b32_e32 v104, v0
	v_mov_b32_e32 v105, v0
	v_mov_b32_e32 v106, v0
	v_mov_b32_e32 v107, v0
	v_mov_b32_e32 v112, v0
	v_mov_b32_e32 v113, v0
	v_mov_b32_e32 v114, v0
	v_mov_b32_e32 v115, v0
	v_mov_b32_e32 v120, v0
	v_mov_b32_e32 v121, v0
	v_mov_b32_e32 v122, v0
	v_mov_b32_e32 v123, v0
	v_mov_b32_e32 v128, v0
	v_mov_b32_e32 v129, v0
	v_mov_b32_e32 v130, v0
	v_mov_b32_e32 v131, v0
	v_mov_b32_e32 v136, v0
	v_mov_b32_e32 v137, v0
	v_mov_b32_e32 v138, v0
	v_mov_b32_e32 v139, v0
	v_mov_b32_e32 v144, v0
	v_mov_b32_e32 v145, v0
	v_mov_b32_e32 v146, v0
	v_mov_b32_e32 v147, v0
	v_mov_b32_e32 v68, v0
	v_mov_b32_e32 v69, v0
	v_mov_b32_e32 v70, v0
	v_mov_b32_e32 v71, v0
	v_mov_b32_e32 v76, v0
	v_mov_b32_e32 v77, v0
	v_mov_b32_e32 v78, v0
	v_mov_b32_e32 v79, v0
	v_mov_b32_e32 v108, v0
	v_mov_b32_e32 v109, v0
	v_mov_b32_e32 v110, v0
	v_mov_b32_e32 v111, v0
	v_mov_b32_e32 v116, v0
	v_mov_b32_e32 v117, v0
	v_mov_b32_e32 v118, v0
	v_mov_b32_e32 v119, v0
	v_mov_b32_e32 v124, v0
	v_mov_b32_e32 v125, v0
	v_mov_b32_e32 v126, v0
	v_mov_b32_e32 v127, v0
	v_mov_b32_e32 v132, v0
	v_mov_b32_e32 v133, v0
	v_mov_b32_e32 v134, v0
	v_mov_b32_e32 v135, v0
	v_mov_b32_e32 v140, v0
	v_mov_b32_e32 v141, v0
	v_mov_b32_e32 v142, v0
	v_mov_b32_e32 v143, v0
	v_mov_b32_e32 v148, v0
	v_mov_b32_e32 v149, v0
	v_mov_b32_e32 v150, v0
	v_mov_b32_e32 v151, v0
	s_branch .LBB0_795

.LBB0_884:
	s_mul_i32 s92, s90, 0x2c0000
	s_and_b64 s[6:7], s[38:39], exec
	s_mul_i32 s93, s91, 0x2c0000
	s_cselect_b32 s6, s92, s8
	s_cselect_b32 s7, s93, s9
	s_add_i32 s8, s8, 0x164000
	s_add_i32 s9, s9, 0x8000
	s_mov_b32 s10, -2
	s_cmp_eq_u32 s88, 1
	s_cbranch_scc0 .Lpeel_p6
	v_mov_b32_e32 v0, 0
	v_mov_b32_e32 v1, v0
	v_mov_b32_e32 v2, v0
	v_mov_b32_e32 v3, v0
	v_mov_b32_e32 v4, v0
	v_mov_b32_e32 v5, v0
	v_mov_b32_e32 v6, v0
	v_mov_b32_e32 v7, v0
	v_mov_b32_e32 v16, v0
	v_mov_b32_e32 v17, v0
	v_mov_b32_e32 v18, v0
	v_mov_b32_e32 v19, v0
	v_mov_b32_e32 v20, v0
	v_mov_b32_e32 v21, v0
	v_mov_b32_e32 v22, v0
	v_mov_b32_e32 v23, v0
	v_mov_b32_e32 v32, v0
	v_mov_b32_e32 v33, v0
	v_mov_b32_e32 v34, v0
	v_mov_b32_e32 v35, v0
	v_mov_b32_e32 v36, v0
	v_mov_b32_e32 v37, v0
	v_mov_b32_e32 v38, v0
	v_mov_b32_e32 v39, v0
	v_mov_b32_e32 v48, v0
	v_mov_b32_e32 v49, v0
	v_mov_b32_e32 v50, v0
	v_mov_b32_e32 v51, v0
	v_mov_b32_e32 v52, v0
	v_mov_b32_e32 v53, v0
	v_mov_b32_e32 v54, v0
	v_mov_b32_e32 v55, v0
	v_mov_b32_e32 v8, v0
	v_mov_b32_e32 v9, v0
	v_mov_b32_e32 v10, v0
	v_mov_b32_e32 v11, v0
	v_mov_b32_e32 v12, v0
	v_mov_b32_e32 v13, v0
	v_mov_b32_e32 v14, v0
	v_mov_b32_e32 v15, v0
	v_mov_b32_e32 v24, v0
	v_mov_b32_e32 v25, v0
	v_mov_b32_e32 v26, v0
	v_mov_b32_e32 v27, v0
	v_mov_b32_e32 v28, v0
	v_mov_b32_e32 v29, v0
	v_mov_b32_e32 v30, v0
	v_mov_b32_e32 v31, v0
	v_mov_b32_e32 v40, v0
	v_mov_b32_e32 v41, v0
	v_mov_b32_e32 v42, v0
	v_mov_b32_e32 v43, v0
	v_mov_b32_e32 v44, v0
	v_mov_b32_e32 v45, v0
	v_mov_b32_e32 v46, v0
	v_mov_b32_e32 v47, v0
	v_mov_b32_e32 v56, v0
	v_mov_b32_e32 v57, v0
	v_mov_b32_e32 v58, v0
	v_mov_b32_e32 v59, v0
	v_mov_b32_e32 v60, v0
	v_mov_b32_e32 v61, v0
	v_mov_b32_e32 v62, v0
	v_mov_b32_e32 v63, v0
	v_mov_b32_e32 v64, v0
	v_mov_b32_e32 v65, v0
	v_mov_b32_e32 v66, v0
	v_mov_b32_e32 v67, v0
	v_mov_b32_e32 v68, v0
	v_mov_b32_e32 v69, v0
	v_mov_b32_e32 v70, v0
	v_mov_b32_e32 v71, v0
	v_mov_b32_e32 v104, v0
	v_mov_b32_e32 v105, v0
	v_mov_b32_e32 v106, v0
	v_mov_b32_e32 v107, v0
	v_mov_b32_e32 v108, v0
	v_mov_b32_e32 v109, v0
	v_mov_b32_e32 v110, v0
	v_mov_b32_e32 v111, v0
	v_mov_b32_e32 v120, v0
	v_mov_b32_e32 v121, v0
	v_mov_b32_e32 v122, v0
	v_mov_b32_e32 v123, v0
	v_mov_b32_e32 v124, v0
	v_mov_b32_e32 v125, v0
	v_mov_b32_e32 v126, v0
	v_mov_b32_e32 v127, v0
	v_mov_b32_e32 v144, v0
	v_mov_b32_e32 v145, v0
	v_mov_b32_e32 v146, v0
	v_mov_b32_e32 v147, v0
	v_mov_b32_e32 v148, v0
	v_mov_b32_e32 v149, v0
	v_mov_b32_e32 v150, v0
	v_mov_b32_e32 v151, v0
	v_mov_b32_e32 v72, v0
	v_mov_b32_e32 v73, v0
	v_mov_b32_e32 v74, v0
	v_mov_b32_e32 v75, v0
	v_mov_b32_e32 v76, v0
	v_mov_b32_e32 v77, v0
	v_mov_b32_e32 v78, v0
	v_mov_b32_e32 v79, v0
	v_mov_b32_e32 v112, v0
	v_mov_b32_e32 v113, v0
	v_mov_b32_e32 v114, v0
	v_mov_b32_e32 v115, v0
	v_mov_b32_e32 v116, v0
	v_mov_b32_e32 v117, v0
	v_mov_b32_e32 v118, v0
	v_mov_b32_e32 v119, v0
	v_mov_b32_e32 v132, v0
	v_mov_b32_e32 v133, v0
	v_mov_b32_e32 v134, v0
	v_mov_b32_e32 v135, v0
	v_mov_b32_e32 v136, v0
	v_mov_b32_e32 v137, v0
	v_mov_b32_e32 v138, v0
	v_mov_b32_e32 v139, v0
	v_mov_b32_e32 v160, v0
	v_mov_b32_e32 v161, v0
	v_mov_b32_e32 v162, v0
	v_mov_b32_e32 v163, v0
	v_mov_b32_e32 v164, v0
	v_mov_b32_e32 v165, v0
	v_mov_b32_e32 v166, v0
	v_mov_b32_e32 v167, v0
	s_branch .LBB0_885
